# st1 + stash stores write-through (sc1) and no L2 writeback before the map0 flag
# speedup vs baseline: 1.0194x; 1.0004x over previous
; template <bool NOMAX>
; __device__ __forceinline__ void diff_unit(const AttnCtx& C, int u, LAS unsigned char* lds) {
;     ...
;     if (umap == 0) {
;         f32x4* st = (f32x4*)(C.stash + (slot * 512 + tidf) * 64);
; #pragma unroll
;         for (int d = 0; d < 4; ++d)
; #pragma unroll
;             for (int gq = 0; gq < 4; ++gq) st[d * 4 + gq] = (f32x4){o[d][4 * gq] * rli[4 * gq], o[d][4 * gq + 1] * rli[4 * gq + 1], o[d][4 * gq + 2] * rli[4 * gq + 2], o[d][4 * gq + 3] * rli[4 * gq + 3]};
;         asm volatile("s_waitcnt vmcnt(0)" ::: "memory");
;         __syncthreads();
;         if (tidf == 0) { __builtin_amdgcn_fence(__ATOMIC_RELEASE, "agent"); asm volatile("s_waitcnt vmcnt(0)" ::: "memory");
;             __hip_atomic_store(C.flags + 16 * (qb * 4 + h), 1u, __ATOMIC_RELAXED, __HIP_MEMORY_SCOPE_AGENT); }
.LBB0_533:
	s_and_b64 vcc, exec, s[6:7]
	s_cbranch_vccz .LBB0_537
	v_ashrrev_i32_e32 v9, 31, v8
	v_lshlrev_b64 v[4:5], 17, v[2:3]
	v_lshl_add_u64 v[4:5], s[12:13], 0, v[4:5]
	v_and_b32_e32 v6, 63, v8
	v_lshrrev_b32_e32 v7, 6, v8
	v_lshlrev_b32_e32 v6, 4, v6
	v_lshl_add_u32 v6, v7, 14, v6
	v_add_u32_e32 v6, 0x1000, v6
	v_mov_b32_e32 v7, 0
	s_mov_b64 s[98:99], 0x2000
	v_lshl_add_u64 v[92:93], v[4:5], 0, v[6:7]
	v_lshl_add_u64 v[254:255], v[92:93], 0, s[98:99]
	v_pk_mul_f32 v[4:5], v[68:69], v[90:91]
	v_pk_mul_f32 v[6:7], v[70:71], v[88:89]
	global_store_dwordx4 v[92:93], v[4:7], off offset:-4096 sc1
	v_cmp_eq_u32_e32 vcc, 0, v8
	s_nop 0
	v_pk_mul_f32 v[4:5], v[72:73], v[14:15]
	v_pk_mul_f32 v[6:7], v[74:75], v[86:87]
	global_store_dwordx4 v[92:93], v[4:7], off offset:-3072 sc1
	s_nop 1
	v_pk_mul_f32 v[4:5], v[76:77], v[84:85]
	v_pk_mul_f32 v[6:7], v[78:79], v[16:17]
	global_store_dwordx4 v[92:93], v[4:7], off offset:-2048 sc1
	s_nop 1
	v_pk_mul_f32 v[4:5], v[80:81], v[12:13]
	v_pk_mul_f32 v[6:7], v[82:83], v[10:11]
	global_store_dwordx4 v[92:93], v[4:7], off offset:-1024 sc1
	s_nop 1
	v_pk_mul_f32 v[4:5], v[52:53], v[90:91]
	v_pk_mul_f32 v[6:7], v[54:55], v[88:89]
	global_store_dwordx4 v[92:93], v[4:7], off sc1
	s_nop 1
	v_pk_mul_f32 v[4:5], v[56:57], v[14:15]
	v_pk_mul_f32 v[6:7], v[58:59], v[86:87]
	global_store_dwordx4 v[92:93], v[4:7], off offset:1024 sc1
	s_nop 1
	v_pk_mul_f32 v[4:5], v[60:61], v[84:85]
	v_pk_mul_f32 v[6:7], v[62:63], v[16:17]
	global_store_dwordx4 v[92:93], v[4:7], off offset:2048 sc1
	s_nop 1
	v_pk_mul_f32 v[4:5], v[64:65], v[12:13]
	v_pk_mul_f32 v[6:7], v[66:67], v[10:11]
	global_store_dwordx4 v[92:93], v[4:7], off offset:3072 sc1
	s_nop 1
	v_pk_mul_f32 v[4:5], v[36:37], v[90:91]
	v_pk_mul_f32 v[6:7], v[38:39], v[88:89]
	global_store_dwordx4 v[254:255], v[4:7], off offset:-4096 sc1
	s_nop 1
	v_pk_mul_f32 v[4:5], v[40:41], v[14:15]
	v_pk_mul_f32 v[6:7], v[42:43], v[86:87]
	global_store_dwordx4 v[254:255], v[4:7], off offset:-3072 sc1
	s_nop 1
	v_pk_mul_f32 v[4:5], v[44:45], v[84:85]
	v_pk_mul_f32 v[6:7], v[46:47], v[16:17]
	global_store_dwordx4 v[254:255], v[4:7], off offset:-2048 sc1
	s_nop 1
	v_pk_mul_f32 v[4:5], v[48:49], v[12:13]
	v_pk_mul_f32 v[6:7], v[50:51], v[10:11]
	global_store_dwordx4 v[254:255], v[4:7], off offset:-1024 sc1
	s_nop 1
	v_pk_mul_f32 v[4:5], v[20:21], v[90:91]
	v_pk_mul_f32 v[6:7], v[22:23], v[88:89]
	global_store_dwordx4 v[254:255], v[4:7], off sc1
	s_nop 1
	v_pk_mul_f32 v[4:5], v[24:25], v[14:15]
	v_pk_mul_f32 v[6:7], v[26:27], v[86:87]
	global_store_dwordx4 v[254:255], v[4:7], off offset:1024 sc1
	s_nop 1
	v_pk_mul_f32 v[4:5], v[28:29], v[84:85]
	v_pk_mul_f32 v[6:7], v[30:31], v[16:17]
	global_store_dwordx4 v[254:255], v[4:7], off offset:2048 sc1
	s_nop 1
	v_pk_mul_f32 v[4:5], v[32:33], v[12:13]
	v_pk_mul_f32 v[6:7], v[34:35], v[10:11]
	global_store_dwordx4 v[254:255], v[4:7], off offset:3072 sc1
	s_waitcnt vmcnt(0)
	s_barrier
	s_and_saveexec_b64 s[4:5], vcc
	s_cbranch_execz .LBB0_536
	v_lshlrev_b32_e32 v2, 4, v94
	s_waitcnt vmcnt(0)
	s_waitcnt vmcnt(0)
	v_lshlrev_b64 v[4:5], 2, v[2:3]
	v_lshl_add_u64 v[4:5], s[14:15], 0, v[4:5]
	global_store_dword v[4:5], v229, off sc1

; template <bool NOMAX>
; __device__ __forceinline__ void diff_unit(const AttnCtx& C, int u, LAS unsigned char* lds) {
;     ...
;     if (umap == 0) {
;         f32x4* st = (f32x4*)(C.stash + (slot * 512 + tidf) * 64);
; #pragma unroll
;         for (int d = 0; d < 4; ++d)
; #pragma unroll
;             for (int gq = 0; gq < 4; ++gq) st[d * 4 + gq] = (f32x4){o[d][4 * gq] * rli[4 * gq], o[d][4 * gq + 1] * rli[4 * gq + 1], o[d][4 * gq + 2] * rli[4 * gq + 2], o[d][4 * gq + 3] * rli[4 * gq + 3]};
;         asm volatile("s_waitcnt vmcnt(0)" ::: "memory");
;         __syncthreads();
;         if (tidf == 0) { __builtin_amdgcn_fence(__ATOMIC_RELEASE, "agent"); asm volatile("s_waitcnt vmcnt(0)" ::: "memory");
;             __hip_atomic_store(C.flags + 16 * (qb * 4 + h), 1u, __ATOMIC_RELAXED, __HIP_MEMORY_SCOPE_AGENT); }
.LBB0_641:
	s_and_b64 vcc, exec, s[4:5]
	s_cbranch_vccz .LBB0_446
	v_ashrrev_i32_e32 v9, 31, v8
	v_lshlrev_b64 v[4:5], 17, v[2:3]
	v_lshl_add_u64 v[4:5], s[12:13], 0, v[4:5]
	v_and_b32_e32 v6, 63, v8
	v_lshrrev_b32_e32 v7, 6, v8
	v_lshlrev_b32_e32 v6, 4, v6
	v_lshl_add_u32 v6, v7, 14, v6
	v_add_u32_e32 v6, 0x1000, v6
	v_mov_b32_e32 v7, 0
	s_mov_b64 s[98:99], 0x2000
	v_lshl_add_u64 v[16:17], v[4:5], 0, v[6:7]
	v_lshl_add_u64 v[254:255], v[16:17], 0, s[98:99]
	v_pk_mul_f32 v[4:5], v[82:83], v[28:29]
	v_pk_mul_f32 v[6:7], v[84:85], v[26:27]
	global_store_dwordx4 v[16:17], v[4:7], off offset:-4096 sc1
	v_cmp_eq_u32_e32 vcc, 0, v8
	s_nop 0
	v_pk_mul_f32 v[4:5], v[86:87], v[14:15]
	v_pk_mul_f32 v[6:7], v[88:89], v[24:25]
	global_store_dwordx4 v[16:17], v[4:7], off offset:-3072 sc1
	s_nop 1
	v_pk_mul_f32 v[4:5], v[90:91], v[22:23]
	v_pk_mul_f32 v[6:7], v[92:93], v[20:21]
	global_store_dwordx4 v[16:17], v[4:7], off offset:-2048 sc1
	s_nop 1
	v_pk_mul_f32 v[4:5], v[94:95], v[12:13]
	v_pk_mul_f32 v[6:7], v[96:97], v[10:11]
	global_store_dwordx4 v[16:17], v[4:7], off offset:-1024 sc1
	s_nop 1
	v_pk_mul_f32 v[4:5], v[66:67], v[28:29]
	v_pk_mul_f32 v[6:7], v[68:69], v[26:27]
	global_store_dwordx4 v[16:17], v[4:7], off sc1
	s_nop 1
	v_pk_mul_f32 v[4:5], v[70:71], v[14:15]
	v_pk_mul_f32 v[6:7], v[72:73], v[24:25]
	global_store_dwordx4 v[16:17], v[4:7], off offset:1024 sc1
	s_nop 1
	v_pk_mul_f32 v[4:5], v[74:75], v[22:23]
	v_pk_mul_f32 v[6:7], v[76:77], v[20:21]
	global_store_dwordx4 v[16:17], v[4:7], off offset:2048 sc1
	s_nop 1
	v_pk_mul_f32 v[4:5], v[78:79], v[12:13]
	v_pk_mul_f32 v[6:7], v[80:81], v[10:11]
	global_store_dwordx4 v[16:17], v[4:7], off offset:3072 sc1
	s_nop 1
	v_pk_mul_f32 v[4:5], v[50:51], v[28:29]
	v_pk_mul_f32 v[6:7], v[52:53], v[26:27]
	global_store_dwordx4 v[254:255], v[4:7], off offset:-4096 sc1
	s_nop 1
	v_pk_mul_f32 v[4:5], v[54:55], v[14:15]
	v_pk_mul_f32 v[6:7], v[56:57], v[24:25]
	global_store_dwordx4 v[254:255], v[4:7], off offset:-3072 sc1
	s_nop 1
	v_pk_mul_f32 v[4:5], v[58:59], v[22:23]
	v_pk_mul_f32 v[6:7], v[60:61], v[20:21]
	global_store_dwordx4 v[254:255], v[4:7], off offset:-2048 sc1
	s_nop 1
	v_pk_mul_f32 v[4:5], v[62:63], v[12:13]
	v_pk_mul_f32 v[6:7], v[64:65], v[10:11]
	global_store_dwordx4 v[254:255], v[4:7], off offset:-1024 sc1
	s_nop 1
	v_pk_mul_f32 v[4:5], v[34:35], v[28:29]
	v_pk_mul_f32 v[6:7], v[36:37], v[26:27]
	global_store_dwordx4 v[254:255], v[4:7], off sc1
	s_nop 1
	v_pk_mul_f32 v[4:5], v[38:39], v[14:15]
	v_pk_mul_f32 v[6:7], v[40:41], v[24:25]
	global_store_dwordx4 v[254:255], v[4:7], off offset:1024 sc1
	s_nop 1
	v_pk_mul_f32 v[4:5], v[42:43], v[22:23]
	v_pk_mul_f32 v[6:7], v[44:45], v[20:21]
	global_store_dwordx4 v[254:255], v[4:7], off offset:2048 sc1
	s_nop 1
	v_pk_mul_f32 v[4:5], v[46:47], v[12:13]
	v_pk_mul_f32 v[6:7], v[48:49], v[10:11]
	global_store_dwordx4 v[254:255], v[4:7], off offset:3072 sc1
	s_waitcnt vmcnt(0)
	s_barrier
	s_and_saveexec_b64 s[2:3], vcc
	s_cbranch_execz .LBB0_445
	v_lshlrev_b32_e32 v2, 4, v19
	s_waitcnt vmcnt(0)
	s_waitcnt vmcnt(0)
	v_lshlrev_b64 v[4:5], 2, v[2:3]
	v_lshl_add_u64 v[4:5], s[14:15], 0, v[4:5]
	global_store_dword v[4:5], v229, off sc1
	s_branch .LBB0_445
